# adds S5 next-chunk u prefetch one chunk ahead (both passes) on top of the previous version
# speedup vs baseline: 1.0122x; 1.0042x over previous
; DI void s5_item(const PRef& p, int l, int b, int g) {
;     ...
;   const float Are = ((const float*)p.in[I_SARE])[(l * 16 + g) * 64 + lane];
;   const float Aim = ((const float*)p.in[I_SAIM])[(l * 16 + g) * 64 + lane];
;   const float delta = expf(((const float*)p.in[I_SLOG])[l * 16 + g]);
;   float cr, ci;
;   {
;     float er = expf(delta * Are); float sn, cs; sincosf(delta * Aim, &sn, &cs);
;     cr = er * cs; ci = er * sn;
;   }
;   float Bre[16], Bim[16];
;   {
;     const float x = cr - 1.f, y = ci, den = 1.f / (Are * Are + Aim * Aim);
;     const float qre = (x * Are + y * Aim) * den, qim = (y * Are - x * Aim) * den;
;     const float* bre = (const float*)p.in[I_SBRE] + ((size_t)(l * 16 + g) * 64 + lane) * 16;
;     const float* bim = (const float*)p.in[I_SBIM] + ((size_t)(l * 16 + g) * 64 + lane) * 16;
; #pragma unroll
;     for (int hh = 0; hh < 16; ++hh) { float br = bre[hh], bi = bim[hh]; Bre[hh] = qre * br - qim * bi; Bim[hh] = qre * bi + qim * br; }
.LBB0_220:
	s_or_b64 exec, exec, s[6:7]
	s_waitcnt vmcnt(0)
	v_mul_f32_e32 v2, v36, v2
	v_mul_f32_e32 v5, 0x3fb8aa3b, v2
	v_fma_f32 v6, v2, s38, -v5
	v_rndne_f32_e32 v7, v5
	v_fmac_f32_e32 v6, 0x32a5705f, v2
	v_sub_f32_e32 v5, v5, v7
	v_add_f32_e32 v5, v5, v6
	v_exp_f32_e32 v5, v5
	v_cvt_i32_f32_e32 v6, v7
	v_cmp_ngt_f32_e32 vcc, s39, v2
	v_xor_b32_e32 v1, v1, v0
	s_movk_i32 s6, 0x1f8
	v_ldexp_f32 v5, v5, v6
	v_cndmask_b32_e32 v5, 0, v5, vcc
	v_cmp_nlt_f32_e32 vcc, s74, v2
	v_mul_f32_e32 v2, v3, v3
	v_cmp_class_f32_e64 s[6:7], v0, s6
	v_cndmask_b32_e32 v34, v240, v5, vcc
	v_mov_b32_e32 v5, 0x3c0881c4
	v_fmamk_f32 v5, v2, 0xb94c1982, v5
	v_fmaak_f32 v5, v2, v5, 0xbe2aaa9d
	v_mul_f32_e32 v5, v2, v5
	v_fmac_f32_e32 v3, v3, v5
	v_mov_b32_e32 v5, 0xbab64f3b
	v_fmamk_f32 v5, v2, 0x37d75334, v5
	v_fmaak_f32 v5, v2, v5, 0x3d2aabf7
	v_fmaak_f32 v5, v2, v5, 0xbf000004
	v_fma_f32 v2, v2, v5, 1.0
	v_lshlrev_b32_e32 v5, 30, v4
	v_and_b32_e32 v4, 1, v4
	v_cmp_eq_u32_e32 vcc, 0, v4
	v_and_b32_e32 v35, 0x80000000, v5
	s_lshl_b32 s29, s29, 12
	v_cndmask_b32_e32 v4, v2, v3, vcc
	v_xor_b32_e32 v38, v1, v4
	v_xor_b32_e32 v1, 0x80000000, v3
	v_cndmask_b32_e32 v39, v1, v2, vcc
	v_pk_mul_f32 v[0:1], v[36:37], v[36:37]
	v_lshlrev_b32_e32 v30, 6, v75
	v_add_f32_e32 v0, v0, v1
	v_div_scale_f32 v1, s[8:9], v0, v0, 1.0
	v_rcp_f32_e32 v2, v1
	s_load_dwordx8 s[8:15], s[18:19], 0xb0
	v_xor_b32_e32 v38, v38, v35
	v_xor_b32_e32 v35, v39, v35
	v_fma_f32 v3, -v1, v2, 1.0
	v_fmac_f32_e32 v2, v3, v2
	v_div_scale_f32 v3, vcc, 1.0, v0, 1.0
	v_mul_f32_e32 v4, v3, v2
	v_fma_f32 v5, -v1, v4, v3
	v_fmac_f32_e32 v4, v5, v2
	s_waitcnt lgkmcnt(0)
	s_add_u32 s8, s8, s29
	v_fma_f32 v1, -v1, v4, v3
	s_addc_u32 s9, s9, 0
	v_div_fmas_f32 v1, v1, v2, v4
	s_add_u32 s10, s10, s29
	v_div_fixup_f32 v16, v1, v0, 1.0
	s_addc_u32 s11, s11, 0
	global_load_dwordx4 v[0:3], v30, s[8:9] offset:48
	global_load_dwordx4 v[8:11], v30, s[8:9] offset:32
	global_load_dwordx4 v[18:21], v30, s[8:9] offset:16
	global_load_dwordx4 v[26:29], v30, s[8:9]
	global_load_dwordx4 v[4:7], v30, s[10:11] offset:48
	global_load_dwordx4 v[12:15], v30, s[10:11] offset:32
	global_load_dwordx4 v[22:25], v30, s[10:11] offset:16
	s_nop 0
	global_load_dwordx4 v[30:33], v30, s[10:11]
	v_cndmask_b32_e64 v39, v237, v38, s[6:7]
	v_cndmask_b32_e64 v38, v237, v35, s[6:7]
	v_pk_mul_f32 v[34:35], v[34:35], v[38:39] op_sel_hi:[0,1]
	v_add_f32_e32 v38, -1.0, v34
	v_mov_b32_e32 v40, v37
	v_mov_b32_e32 v42, v35
	v_mov_b32_e32 v43, v38
	v_mov_b32_e32 v39, v35
	v_pk_mul_f32 v[40:41], v[40:41], v[42:43] op_sel_hi:[0,1]
	v_pk_fma_f32 v[42:43], v[36:37], v[38:39], v[40:41]
	v_pk_fma_f32 v[36:37], v[36:37], v[38:39], v[40:41] op_sel_hi:[0,1,1] neg_lo:[0,0,1] neg_hi:[0,0,1]
	v_mov_b32_e32 v43, v37
	v_pk_mul_f32 v[70:71], v[16:17], v[42:43] op_sel_hi:[0,1]
	v_and_b32_e32 v82, 15, v74
	s_add_u32 s6, s12, s29
	s_addc_u32 s7, s13, 0
	s_barrier
; DI unsigned pack2(float a, float b) { f32v2 v = {a, b}; return __builtin_bit_cast(unsigned, __builtin_convertvector(v, bf16v2)); }
; DI void s5_item(const PRef& p, int l, int b, int g) {
;     ...
;     for (int hh = 0; hh < 16; ++hh) { float br = bre[hh], bi = bim[hh]; Bre[hh] = qre * br - qim * bi; Bim[hh] = qre * bi + qim * br; }
;   }
;   __syncthreads();
;   bf16x8 cf[4];
;   {
;     const int hq = lane & 15, q4 = lane >> 4;
;     const float* cre = (const float*)p.in[I_SCRE] + ((size_t)(l * 16 + g) * 16 + hq) * 64;
;     const float* cim = (const float*)p.in[I_SCIM] + ((size_t)(l * 16 + g) * 16 + hq) * 64;
; #pragma unroll
;     for (int s4 = 0; s4 < 4; ++s4) {
;       const float4 re = *reinterpret_cast<const float4*>(cre + 16 * s4 + 4 * q4);
;       const float4 im = *reinterpret_cast<const float4*>(cim + 16 * s4 + 4 * q4);
;       cf[s4] = __builtin_bit_cast(bf16x8, (u32x4{pack2(re.x, -im.x), pack2(re.y, -im.y), pack2(re.z, -im.z), pack2(re.w, -im.w)}));
;     }
;   }
;   const int tbase = b * SEQ + w * 512;
;   float* uw = uL + w * 256;
;   auto load_u = [&](int ch) {
;     const int tt = lane >> 2, c4 = (lane & 3) * 4;
;     uint2 raw = *reinterpret_cast<const uint2*>(s5 + (size_t)(tbase + ch * 16 + tt) * 256 + g * 16 + c4);
;     float4 f; f.x = __uint_as_float(raw.x << 16); f.y = __uint_as_float(raw.x & 0xffff0000u);
;     f.z = __uint_as_float(raw.y << 16); f.w = __uint_as_float(raw.y & 0xffff0000u);
;     *reinterpret_cast<float4*>(uw + tt * 16 + c4) = f;
;   };
;   float xr = 0.f, xi = 0.f;
;   for (int ch = 0; ch < 32; ++ch) {
;     __syncthreads();
;     load_u(ch);
	v_ashrrev_i32_e32 v81, 6, v74
	v_lshrrev_b32_e32 v84, 2, v75
	v_mov_b32_e32 v72, 0
	v_lshl_add_u32 v78, v81, 10, 16
	s_mov_b32 s27, 0
	v_mov_b32_e32 v73, v72
	s_waitcnt vmcnt(0)
	v_pk_mul_f32 v[40:41], v[30:31], v[70:71] op_sel:[0,1] op_sel_hi:[1,0]
	v_pk_mul_f32 v[30:31], v[30:31], v[70:71]
	v_pk_fma_f32 v[38:39], v[26:27], v[70:71], v[40:41] neg_lo:[0,0,1] neg_hi:[0,0,1]
	v_pk_fma_f32 v[36:37], v[26:27], v[70:71], v[30:31] op_sel:[1,0,1] op_sel_hi:[0,1,0] neg_lo:[0,0,1] neg_hi:[0,0,1]
	v_pk_fma_f32 v[30:31], v[26:27], v[70:71], v[30:31] op_sel:[1,0,1] op_sel_hi:[0,1,0]
	v_pk_fma_f32 v[26:27], v[26:27], v[70:71], v[40:41]
	v_mov_b32_e32 v16, v33
	v_mov_b32_e32 v39, v27
	v_pk_mul_f32 v[26:27], v[32:33], v[70:71] op_sel:[0,1] op_sel_hi:[0,0]
	v_pk_fma_f32 v[40:41], v[28:29], v[70:71], v[26:27] neg_lo:[0,0,1] neg_hi:[0,0,1]
	v_pk_fma_f32 v[26:27], v[28:29], v[70:71], v[26:27] op_sel_hi:[0,1,1]
	v_mov_b32_e32 v41, v27
	v_pk_mul_f32 v[26:27], v[16:17], v[70:71] op_sel:[0,1] op_sel_hi:[0,0]
	v_mov_b32_e32 v16, v29
	v_mov_b32_e32 v28, v29
	v_pk_fma_f32 v[42:43], v[16:17], v[70:71], v[26:27] neg_lo:[0,0,1] neg_hi:[0,0,1]
	v_pk_fma_f32 v[26:27], v[28:29], v[70:71], v[26:27] op_sel_hi:[0,1,1]
	v_mov_b32_e32 v43, v27
	v_pk_mul_f32 v[26:27], v[22:23], v[70:71] op_sel:[0,1] op_sel_hi:[1,0]
	v_pk_mul_f32 v[22:23], v[70:71], v[22:23]
	v_pk_fma_f32 v[46:47], v[18:19], v[70:71], v[26:27] neg_lo:[0,0,1] neg_hi:[0,0,1]
	v_pk_fma_f32 v[44:45], v[18:19], v[70:71], v[22:23] op_sel:[1,0,1] op_sel_hi:[0,1,0] neg_lo:[0,0,1] neg_hi:[0,0,1]
	v_pk_fma_f32 v[22:23], v[18:19], v[70:71], v[22:23] op_sel:[1,0,1] op_sel_hi:[0,1,0]
	v_pk_fma_f32 v[18:19], v[18:19], v[70:71], v[26:27]
	v_mov_b32_e32 v16, v25
	v_mov_b32_e32 v47, v19
	v_pk_mul_f32 v[18:19], v[70:71], v[24:25] op_sel:[1,0] op_sel_hi:[0,0]
	v_pk_fma_f32 v[48:49], v[70:71], v[20:21], v[18:19] neg_lo:[0,0,1] neg_hi:[0,0,1]
	v_pk_fma_f32 v[18:19], v[70:71], v[20:21], v[18:19] op_sel_hi:[1,0,1]
	v_mov_b32_e32 v20, v21
	v_mov_b32_e32 v49, v19
	v_pk_mul_f32 v[18:19], v[70:71], v[16:17] op_sel:[1,0] op_sel_hi:[0,0]
	v_mov_b32_e32 v16, v21
	v_pk_fma_f32 v[50:51], v[70:71], v[16:17], v[18:19] neg_lo:[0,0,1] neg_hi:[0,0,1]
	v_pk_fma_f32 v[18:19], v[70:71], v[20:21], v[18:19] op_sel_hi:[1,0,1]
	v_lshlrev_b32_e32 v16, 8, v82
	v_mov_b32_e32 v51, v19
	v_pk_mul_f32 v[18:19], v[70:71], v[12:13] op_sel:[1,0] op_sel_hi:[0,1]
	v_pk_mul_f32 v[12:13], v[70:71], v[12:13]
	v_pk_fma_f32 v[54:55], v[70:71], v[8:9], v[18:19] neg_lo:[0,0,1] neg_hi:[0,0,1]
	v_pk_fma_f32 v[52:53], v[70:71], v[8:9], v[12:13] op_sel:[0,1,1] op_sel_hi:[1,0,0] neg_lo:[0,0,1] neg_hi:[0,0,1]
	v_pk_fma_f32 v[12:13], v[70:71], v[8:9], v[12:13] op_sel:[0,1,1] op_sel_hi:[1,0,0]
	v_pk_fma_f32 v[8:9], v[70:71], v[8:9], v[18:19]
	v_mov_b32_e32 v12, v11
	v_mov_b32_e32 v55, v9
	v_pk_mul_f32 v[8:9], v[70:71], v[14:15] op_sel:[1,0] op_sel_hi:[0,0]
	v_pk_fma_f32 v[56:57], v[70:71], v[10:11], v[8:9] neg_lo:[0,0,1] neg_hi:[0,0,1]
	v_pk_fma_f32 v[8:9], v[70:71], v[10:11], v[8:9] op_sel_hi:[1,0,1]
	v_mov_b32_e32 v10, v11
	v_mov_b32_e32 v8, v15
	v_mov_b32_e32 v57, v9
	v_pk_mul_f32 v[8:9], v[70:71], v[8:9] op_sel:[1,0] op_sel_hi:[0,0]
	v_pk_fma_f32 v[58:59], v[70:71], v[10:11], v[8:9] neg_lo:[0,0,1] neg_hi:[0,0,1]
	v_pk_fma_f32 v[8:9], v[70:71], v[12:13], v[8:9] op_sel_hi:[1,0,1]
	v_mov_b32_e32 v37, v31
	v_mov_b32_e32 v59, v9
	v_pk_mul_f32 v[8:9], v[70:71], v[4:5] op_sel:[1,0] op_sel_hi:[0,1]
	v_pk_mul_f32 v[4:5], v[70:71], v[4:5]
	v_pk_fma_f32 v[62:63], v[70:71], v[0:1], v[8:9] neg_lo:[0,0,1] neg_hi:[0,0,1]
	v_pk_fma_f32 v[60:61], v[70:71], v[0:1], v[4:5] op_sel:[0,1,1] op_sel_hi:[1,0,0] neg_lo:[0,0,1] neg_hi:[0,0,1]
	v_pk_fma_f32 v[4:5], v[70:71], v[0:1], v[4:5] op_sel:[0,1,1] op_sel_hi:[1,0,0]
	v_pk_fma_f32 v[0:1], v[70:71], v[0:1], v[8:9]
	v_mov_b32_e32 v4, v3
	v_mov_b32_e32 v63, v1
	v_pk_mul_f32 v[0:1], v[70:71], v[6:7] op_sel:[1,0] op_sel_hi:[0,0]
	v_pk_fma_f32 v[64:65], v[70:71], v[2:3], v[0:1] neg_lo:[0,0,1] neg_hi:[0,0,1]
	v_pk_fma_f32 v[0:1], v[70:71], v[2:3], v[0:1] op_sel_hi:[1,0,1]
	v_mov_b32_e32 v2, v3
	v_mov_b32_e32 v0, v7
	v_mov_b32_e32 v65, v1
	v_pk_mul_f32 v[0:1], v[70:71], v[0:1] op_sel:[1,0] op_sel_hi:[0,0]
	v_pk_fma_f32 v[66:67], v[70:71], v[2:3], v[0:1] neg_lo:[0,0,1] neg_hi:[0,0,1]
	v_pk_fma_f32 v[0:1], v[70:71], v[4:5], v[0:1] op_sel_hi:[1,0,1]
	v_mov_b32_e32 v53, v13
	v_mov_b32_e32 v67, v1
	v_lshl_add_u64 v[0:1], s[6:7], 0, v[16:17]
	s_add_u32 s6, s14, s29
	s_addc_u32 s7, s15, 0
	v_lshl_add_u64 v[2:3], s[6:7], 0, v[16:17]
	v_and_b32_e32 v16, 48, v74
	v_lshl_add_u64 v[12:13], v[0:1], 0, v[16:17]
	v_lshl_add_u64 v[30:31], v[2:3], 0, v[16:17]
	v_mov_b32_e32 v45, v23
	v_mov_b32_e32 v61, v5
	global_load_dwordx4 v[0:3], v[12:13], off
	global_load_dwordx4 v[18:21], v[30:31], off
	global_load_dwordx4 v[4:7], v[12:13], off offset:64
	global_load_dwordx4 v[26:29], v[30:31], off offset:64
	global_load_dwordx4 v[8:11], v[12:13], off offset:128
	global_load_dwordx4 v[22:25], v[30:31], off offset:128
	s_nop 0
	global_load_dwordx4 v[12:15], v[12:13], off offset:192
	s_nop 0
	global_load_dwordx4 v[30:33], v[30:31], off offset:192
	s_lshl_b32 s6, s26, 8
	s_and_b32 s6, s6, 0xf000
	s_addk_i32 s6, 0xc000
	v_lshl_add_u32 v83, v81, 9, s6
	s_lshl_b32 s10, s28, 4
	s_lshl_b32 s6, s28, 5
	v_and_b32_e32 v70, 12, v68
	s_add_u32 s6, s2, s6
	s_addc_u32 s7, s3, 0
	v_lshlrev_b32_e32 v16, 1, v70
	v_lshl_add_u64 v[68:69], s[6:7], 0, v[16:17]
	s_mov_b64 s[6:7], 0xf000000
	v_lshlrev_b32_e32 v16, 6, v84
	v_lshlrev_b32_e32 v70, 2, v70
	v_or_b32_e32 v79, v83, v84
	v_lshl_add_u64 v[68:69], v[68:69], 0, s[6:7]
	v_add3_u32 v80, v78, v16, v70
	v_pk_mov_b32 v[70:71], v[34:35], v[34:35] op_sel:[1,0]
	v_lshl_add_u32 v204, s27, 4, v79
	v_ashrrev_i32_e32 v205, 31, v204
	v_lshlrev_b64 v[204:205], 9, v[204:205]
	v_lshl_add_u64 v[204:205], v[68:69], 0, v[204:205]
	global_load_dwordx2 v[206:207], v[204:205], off
.LBB0_221:
	s_barrier
	s_mov_b32 s6, 0
	s_waitcnt vmcnt(0)
	v_lshlrev_b32_e32 v86, 16, v206
	v_and_b32_e32 v87, 0xffff0000, v206
	v_lshlrev_b32_e32 v88, 16, v207
	v_and_b32_e32 v89, 0xffff0000, v207
	ds_write_b128 v80, v[86:89]
	v_lshl_add_u32 v204, s27, 4, v79
	v_add_u32_e32 v204, 16, v204
	v_ashrrev_i32_e32 v205, 31, v204
	v_lshlrev_b64 v[204:205], 9, v[204:205]
	v_lshl_add_u64 v[204:205], v[68:69], 0, v[204:205]
	global_load_dwordx2 v[206:207], v[204:205], off
	s_waitcnt lgkmcnt(0)
	s_barrier

; DI unsigned pack2(float a, float b) { f32v2 v = {a, b}; return __builtin_bit_cast(unsigned, __builtin_convertvector(v, bf16v2)); }
; DI void s5_item(const PRef& p, int l, int b, int g) {
;     ...
;     const int hq = lane & 15, q4 = lane >> 4;
;     const float* cre = (const float*)p.in[I_SCRE] + ((size_t)(l * 16 + g) * 16 + hq) * 64;
;     const float* cim = (const float*)p.in[I_SCIM] + ((size_t)(l * 16 + g) * 16 + hq) * 64;
; #pragma unroll
;     for (int s4 = 0; s4 < 4; ++s4) {
;       const float4 re = *reinterpret_cast<const float4*>(cre + 16 * s4 + 4 * q4);
;       const float4 im = *reinterpret_cast<const float4*>(cim + 16 * s4 + 4 * q4);
;       cf[s4] = __builtin_bit_cast(bf16x8, (u32x4{pack2(re.x, -im.x), pack2(re.y, -im.y), pack2(re.z, -im.z), pack2(re.w, -im.w)}));
;     }
;     ...
;   float* xw = xL + w * (16 * 66 * 2);
;   const int ot = lane & 15, oh = (lane >> 4) * 4;
;   const float* dsk = (const float*)p.in[I_SD] + l * 256 + g * 16 + oh;
;   const float d0 = dsk[0], d1 = dsk[1], d2 = dsk[2], d3 = dsk[3];
.LBB0_230:
	s_or_b64 exec, exec, s[6:7]
	v_xor_b32_e32 v24, 0x80000000, v24
	s_movk_i32 s6, 0x2100
	v_cvt_pk_bf16_f32 v10, v10, v24
	v_mul_lo_u32 v24, v81, s6
	s_load_dwordx2 s[6:7], s[18:19], 0xd0
	v_xor_b32_e32 v16, 0x80000000, v18
	v_xor_b32_e32 v18, 0x80000000, v19
	v_xor_b32_e32 v19, 0x80000000, v20
	v_xor_b32_e32 v20, 0x80000000, v21
	s_waitcnt lgkmcnt(0)
	s_add_u32 s6, s6, s25
	v_xor_b32_e32 v21, 0x80000000, v26
	v_xor_b32_e32 v26, 0x80000000, v27
	s_addc_u32 s7, s7, 0
	s_lshl_b32 s8, s10, 2
	v_cvt_pk_bf16_f32 v5, v5, v26
	v_and_b32_e32 v26, 12, v84
	s_add_u32 s6, s6, s8
	v_cvt_pk_bf16_f32 v0, v0, v16
	s_addc_u32 s7, s7, 0
	v_lshlrev_b32_e32 v16, 2, v26
	v_cvt_pk_bf16_f32 v1, v1, v18
	v_cvt_pk_bf16_f32 v2, v2, v19
	v_cvt_pk_bf16_f32 v3, v3, v20
	v_cvt_pk_bf16_f32 v4, v4, v21
	global_load_dwordx4 v[18:21], v16, s[6:7]
	v_xor_b32_e32 v22, 0x80000000, v22
	s_lshl_b32 s6, s10, 1
	v_xor_b32_e32 v27, 0x80000000, v28
	v_xor_b32_e32 v28, 0x80000000, v29
	v_xor_b32_e32 v29, 0x80000000, v30
	v_xor_b32_e32 v30, 0x80000000, v31
	v_xor_b32_e32 v31, 0x80000000, v32
	v_xor_b32_e32 v32, 0x80000000, v33
	v_cvt_pk_bf16_f32 v8, v8, v22
	v_lshlrev_b32_e32 v22, 6, v82
	s_add_u32 s2, s2, s6
	v_xor_b32_e32 v23, 0x80000000, v23
	v_cvt_pk_bf16_f32 v15, v15, v32
	v_add3_u32 v32, v78, v22, v16
	s_addc_u32 s3, s3, 0
	v_lshlrev_b32_e32 v16, 1, v26
	v_xor_b32_e32 v25, 0x80000000, v25
	v_cvt_pk_bf16_f32 v6, v6, v27
	v_cvt_pk_bf16_f32 v9, v9, v23
	v_mul_u32_u24_e32 v27, 0x42, v82
	v_lshl_add_u64 v[22:23], s[2:3], 0, v[16:17]
	s_mov_b64 s[2:3], 0x3000000
	v_cvt_pk_bf16_f32 v11, v11, v25
	v_cvt_pk_bf16_f32 v13, v13, v30
	v_cvt_pk_bf16_f32 v14, v14, v31
	v_add_u32_e32 v25, 16, v24
	v_lshl_add_u64 v[30:31], v[22:23], 0, s[2:3]
	v_add_lshl_u32 v22, v26, v27, 3
	v_readlane_b32 s2, v254, 0
	v_cvt_pk_bf16_f32 v7, v7, v28
	v_cvt_pk_bf16_f32 v12, v12, v29
	v_or_b32_e32 v33, v83, v82
	v_add3_u32 v16, v24, v85, s2
	s_mov_b32 s6, 0
	v_add_u32_e32 v74, v25, v22
	s_lshl_b32 s7, s6, 4
	v_or_b32_e32 v204, s7, v79
	v_ashrrev_i32_e32 v205, 31, v204
	v_lshlrev_b64 v[204:205], 9, v[204:205]
	v_lshl_add_u64 v[204:205], v[68:69], 0, v[204:205]
	global_load_dwordx2 v[206:207], v[204:205], off
	s_branch .LBB0_232

; DI void s5_item(const PRef& p, int l, int b, int g) {
;     ...
;   auto load_u = [&](int ch) {
;     const int tt = lane >> 2, c4 = (lane & 3) * 4;
;     uint2 raw = *reinterpret_cast<const uint2*>(s5 + (size_t)(tbase + ch * 16 + tt) * 256 + g * 16 + c4);
;     float4 f; f.x = __uint_as_float(raw.x << 16); f.y = __uint_as_float(raw.x & 0xffff0000u);
;     f.z = __uint_as_float(raw.y << 16); f.w = __uint_as_float(raw.y & 0xffff0000u);
;     *reinterpret_cast<float4*>(uw + tt * 16 + c4) = f;
;   };
;     ...
;   for (int ch = 0; ch < 32; ++ch) {
;     __syncthreads();
;     load_u(ch);
;     __syncthreads();
.LBB0_232:
	s_lshl_b32 s7, s6, 4
	s_barrier
	s_mov_b32 s2, 0
	s_waitcnt vmcnt(1)
	s_cmp_lg_u32 s6, 0
	s_cbranch_scc1 .Ls5p2_w
	s_waitcnt vmcnt(0)
.Ls5p2_w:
	v_lshlrev_b32_e32 v22, 16, v206
	v_and_b32_e32 v23, 0xffff0000, v206
	v_lshlrev_b32_e32 v24, 16, v207
	v_and_b32_e32 v25, 0xffff0000, v207
	ds_write_b128 v80, v[22:25]
	v_mov_b32_e32 v22, v16
	v_or_b32_e32 v204, s7, v79
	v_add_u32_e32 v204, 16, v204
	v_ashrrev_i32_e32 v205, 31, v204
	v_lshlrev_b64 v[204:205], 9, v[204:205]
	v_lshl_add_u64 v[204:205], v[68:69], 0, v[204:205]
	global_load_dwordx2 v[206:207], v[204:205], off
	s_waitcnt lgkmcnt(0)
	s_barrier
